# pool slab staging: 5 serialized load/wait/ds_write iterations batched into 5 loads + one wait
# speedup vs baseline: 1.0092x; 1.0092x over previous
.LBB0_330:
	s_or_b64 exec, exec, s[0:1]
	s_movk_i32 s0, 0xa00
	s_sub_i32 s60, s49, s54
	v_cmp_gt_i32_e32 vcc, s0, v156
	s_and_saveexec_b64 s[0:1], vcc
	s_cbranch_execz .LBB0_335
	v_lshlrev_b32_e32 v0, 4, v155
	s_add_i32 s23, s60, -8
	v_add_u32_e32 v14, 0, v0
	v_lshl_add_u64 v[16:17], s[24:25], 0, v[0:1]
	v_ashrrev_i32_e32 v227, 5, v156
	v_add_u32_e32 v228, s23, v227
	v_mad_u32_u24 v226, v227, s69, v14
	v_add_u32_e32 v232, s54, v228
	v_mad_i64_i32 v[230:231], s[62:63], v232, s77, v[16:17]
	v_mov_b32_e32 v206, 0
	v_mov_b32_e32 v207, 0
	v_mov_b32_e32 v208, 0
	v_mov_b32_e32 v209, 0
	v_cmp_gt_u32_e32 vcc, s51, v228
	s_and_saveexec_b64 s[30:31], vcc
	global_load_dwordx4 v[206:209], v[230:231], off offset:1536
	s_mov_b64 exec, s[30:31]
	v_add_co_u32_e32 v230, vcc, 0x28000, v230
	s_nop 1
	v_addc_co_u32_e32 v231, vcc, 0, v231, vcc
	v_mov_b32_e32 v210, 0
	v_mov_b32_e32 v211, 0
	v_mov_b32_e32 v212, 0
	v_mov_b32_e32 v213, 0
	v_add_u32_e32 v229, 16, v228
	v_cmp_gt_u32_e32 vcc, s51, v229
	s_and_saveexec_b64 s[30:31], vcc
	global_load_dwordx4 v[210:213], v[230:231], off offset:1536
	s_mov_b64 exec, s[30:31]
	v_add_co_u32_e32 v230, vcc, 0x28000, v230
	s_nop 1
	v_addc_co_u32_e32 v231, vcc, 0, v231, vcc
	v_mov_b32_e32 v214, 0
	v_mov_b32_e32 v215, 0
	v_mov_b32_e32 v216, 0
	v_mov_b32_e32 v217, 0
	v_add_u32_e32 v229, 32, v228
	v_cmp_gt_u32_e32 vcc, s51, v229
	s_and_saveexec_b64 s[30:31], vcc
	global_load_dwordx4 v[214:217], v[230:231], off offset:1536
	s_mov_b64 exec, s[30:31]
	v_add_co_u32_e32 v230, vcc, 0x28000, v230
	s_nop 1
	v_addc_co_u32_e32 v231, vcc, 0, v231, vcc
	v_mov_b32_e32 v218, 0
	v_mov_b32_e32 v219, 0
	v_mov_b32_e32 v220, 0
	v_mov_b32_e32 v221, 0
	v_add_u32_e32 v229, 48, v228
	v_cmp_gt_u32_e32 vcc, s51, v229
	s_and_saveexec_b64 s[30:31], vcc
	global_load_dwordx4 v[218:221], v[230:231], off offset:1536
	s_mov_b64 exec, s[30:31]
	v_add_co_u32_e32 v230, vcc, 0x28000, v230
	s_nop 1
	v_addc_co_u32_e32 v231, vcc, 0, v231, vcc
	v_mov_b32_e32 v222, 0
	v_mov_b32_e32 v223, 0
	v_mov_b32_e32 v224, 0
	v_mov_b32_e32 v225, 0
	v_add_u32_e32 v229, 64, v228
	v_cmp_gt_u32_e32 vcc, s51, v229
	s_and_saveexec_b64 s[30:31], vcc
	global_load_dwordx4 v[222:225], v[230:231], off offset:1536
	s_mov_b64 exec, s[30:31]
	s_waitcnt vmcnt(0)
	ds_write_b128 v226, v[206:209]
	ds_write_b128 v226, v[210:213] offset:8448
	ds_write_b128 v226, v[214:217] offset:16896
	ds_write_b128 v226, v[218:221] offset:25344
	ds_write_b128 v226, v[222:225] offset:33792

.LBB0_341:
	s_or_b64 exec, exec, s[0:1]
	s_movk_i32 s0, 0x900
	s_sub_i32 s60, s49, s54
	v_cmp_gt_i32_e32 vcc, s0, v156
	s_and_saveexec_b64 s[0:1], vcc
	s_cbranch_execz .LBB0_346
	v_lshlrev_b32_e32 v0, 4, v155
	s_add_i32 s23, s60, -4
	v_add_u32_e32 v14, 0, v0
	v_lshl_add_u64 v[16:17], s[24:25], 0, v[0:1]
	v_ashrrev_i32_e32 v227, 5, v156
	v_add_u32_e32 v228, s23, v227
	v_mad_u32_u24 v226, v227, s69, v14
	v_add_u32_e32 v232, s54, v228
	v_mad_i64_i32 v[230:231], s[62:63], v232, s77, v[16:17]
	v_mov_b32_e32 v206, 0
	v_mov_b32_e32 v207, 0
	v_mov_b32_e32 v208, 0
	v_mov_b32_e32 v209, 0
	v_cmp_gt_u32_e32 vcc, s51, v228
	s_and_saveexec_b64 s[30:31], vcc
	global_load_dwordx4 v[206:209], v[230:231], off offset:1024
	s_mov_b64 exec, s[30:31]
	v_add_co_u32_e32 v230, vcc, 0x28000, v230
	s_nop 1
	v_addc_co_u32_e32 v231, vcc, 0, v231, vcc
	v_mov_b32_e32 v210, 0
	v_mov_b32_e32 v211, 0
	v_mov_b32_e32 v212, 0
	v_mov_b32_e32 v213, 0
	v_add_u32_e32 v229, 16, v228
	v_cmp_gt_u32_e32 vcc, s51, v229
	s_and_saveexec_b64 s[30:31], vcc
	global_load_dwordx4 v[210:213], v[230:231], off offset:1024
	s_mov_b64 exec, s[30:31]
	v_add_co_u32_e32 v230, vcc, 0x28000, v230
	s_nop 1
	v_addc_co_u32_e32 v231, vcc, 0, v231, vcc
	v_mov_b32_e32 v214, 0
	v_mov_b32_e32 v215, 0
	v_mov_b32_e32 v216, 0
	v_mov_b32_e32 v217, 0
	v_add_u32_e32 v229, 32, v228
	v_cmp_gt_u32_e32 vcc, s51, v229
	s_and_saveexec_b64 s[30:31], vcc
	global_load_dwordx4 v[214:217], v[230:231], off offset:1024
	s_mov_b64 exec, s[30:31]
	v_add_co_u32_e32 v230, vcc, 0x28000, v230
	s_nop 1
	v_addc_co_u32_e32 v231, vcc, 0, v231, vcc
	v_mov_b32_e32 v218, 0
	v_mov_b32_e32 v219, 0
	v_mov_b32_e32 v220, 0
	v_mov_b32_e32 v221, 0
	v_add_u32_e32 v229, 48, v228
	v_cmp_gt_u32_e32 vcc, s51, v229
	s_and_saveexec_b64 s[30:31], vcc
	global_load_dwordx4 v[218:221], v[230:231], off offset:1024
	s_mov_b64 exec, s[30:31]
	v_add_co_u32_e32 v230, vcc, 0x28000, v230
	s_nop 1
	v_addc_co_u32_e32 v231, vcc, 0, v231, vcc
	v_mov_b32_e32 v222, 0
	v_mov_b32_e32 v223, 0
	v_mov_b32_e32 v224, 0
	v_mov_b32_e32 v225, 0
	v_add_u32_e32 v229, 64, v228
	v_cmp_gt_u32_e32 vcc, s51, v229
	s_and_saveexec_b64 s[30:31], vcc
	global_load_dwordx4 v[222:225], v[230:231], off offset:1024
	s_mov_b64 exec, s[30:31]
	s_waitcnt vmcnt(0)
	ds_write_b128 v226, v[206:209]
	ds_write_b128 v226, v[210:213] offset:8448
	ds_write_b128 v226, v[214:217] offset:16896
	ds_write_b128 v226, v[218:221] offset:25344
	ds_write_b128 v226, v[222:225] offset:33792

.LBB0_354:
	s_or_b64 exec, exec, s[28:29]
	s_movk_i32 s0, 0x840
	s_sub_i32 s55, s49, s54
	v_cmp_gt_i32_e32 vcc, s0, v156
	s_and_saveexec_b64 s[0:1], vcc
	s_cbranch_execz .LBB0_359
	v_lshlrev_b32_e32 v10, 4, v155
	v_mov_b32_e32 v11, v1
	s_add_i32 s23, s55, -1
	v_lshl_add_u64 v[14:15], s[24:25], 0, v[10:11]
	v_add_u32_e32 v16, 0, v10
	v_ashrrev_i32_e32 v227, 5, v156
	v_add_u32_e32 v228, s23, v227
	v_mad_u32_u24 v226, v227, s69, v16
	v_add_u32_e32 v232, s54, v228
	v_mad_i64_i32 v[230:231], s[62:63], v232, s77, v[14:15]
	v_mov_b32_e32 v206, 0
	v_mov_b32_e32 v207, 0
	v_mov_b32_e32 v208, 0
	v_mov_b32_e32 v209, 0
	v_cmp_gt_u32_e32 vcc, s51, v228
	s_and_saveexec_b64 s[30:31], vcc
	global_load_dwordx4 v[206:209], v[230:231], off
	s_mov_b64 exec, s[30:31]
	v_add_co_u32_e32 v230, vcc, 0x28000, v230
	s_nop 1
	v_addc_co_u32_e32 v231, vcc, 0, v231, vcc
	v_mov_b32_e32 v210, 0
	v_mov_b32_e32 v211, 0
	v_mov_b32_e32 v212, 0
	v_mov_b32_e32 v213, 0
	v_add_u32_e32 v229, 16, v228
	v_cmp_gt_u32_e32 vcc, s51, v229
	s_and_saveexec_b64 s[30:31], vcc
	global_load_dwordx4 v[210:213], v[230:231], off
	s_mov_b64 exec, s[30:31]
	v_add_co_u32_e32 v230, vcc, 0x28000, v230
	s_nop 1
	v_addc_co_u32_e32 v231, vcc, 0, v231, vcc
	v_mov_b32_e32 v214, 0
	v_mov_b32_e32 v215, 0
	v_mov_b32_e32 v216, 0
	v_mov_b32_e32 v217, 0
	v_add_u32_e32 v229, 32, v228
	v_cmp_gt_u32_e32 vcc, s51, v229
	s_and_saveexec_b64 s[30:31], vcc
	global_load_dwordx4 v[214:217], v[230:231], off
	s_mov_b64 exec, s[30:31]
	v_add_co_u32_e32 v230, vcc, 0x28000, v230
	s_nop 1
	v_addc_co_u32_e32 v231, vcc, 0, v231, vcc
	v_mov_b32_e32 v218, 0
	v_mov_b32_e32 v219, 0
	v_mov_b32_e32 v220, 0
	v_mov_b32_e32 v221, 0
	v_add_u32_e32 v229, 48, v228
	v_cmp_gt_u32_e32 vcc, s51, v229
	s_and_saveexec_b64 s[30:31], vcc
	global_load_dwordx4 v[218:221], v[230:231], off
	s_mov_b64 exec, s[30:31]
	v_add_co_u32_e32 v230, vcc, 0x28000, v230
	s_nop 1
	v_addc_co_u32_e32 v231, vcc, 0, v231, vcc
	v_mov_b32_e32 v222, 0
	v_mov_b32_e32 v223, 0
	v_mov_b32_e32 v224, 0
	v_mov_b32_e32 v225, 0
	v_add_u32_e32 v229, 64, v228
	v_cmp_gt_u32_e32 vcc, s51, v229
	s_and_saveexec_b64 s[30:31], vcc
	global_load_dwordx4 v[222:225], v[230:231], off
	s_mov_b64 exec, s[30:31]
	s_waitcnt vmcnt(0)
	ds_write_b128 v226, v[206:209]
	ds_write_b128 v226, v[210:213] offset:8448
	ds_write_b128 v226, v[214:217] offset:16896
	ds_write_b128 v226, v[218:221] offset:25344
	ds_write_b128 v226, v[222:225] offset:33792

.LBB0_365:
	s_or_b64 exec, exec, s[0:1]
	s_movk_i32 s0, 0x880
	s_sub_i32 s55, s49, s54
	v_cmp_gt_i32_e32 vcc, s0, v156
	s_and_saveexec_b64 s[0:1], vcc
	s_cbranch_execz .LBB0_370
	v_lshlrev_b32_e32 v0, 4, v155
	s_add_i32 s23, s55, -2
	v_add_u32_e32 v14, 0, v0
	v_lshl_add_u64 v[16:17], s[24:25], 0, v[0:1]
	v_ashrrev_i32_e32 v227, 5, v156
	v_add_u32_e32 v228, s23, v227
	v_mad_u32_u24 v226, v227, s69, v14
	v_add_u32_e32 v232, s54, v228
	v_mad_i64_i32 v[230:231], s[62:63], v232, s77, v[16:17]
	v_mov_b32_e32 v206, 0
	v_mov_b32_e32 v207, 0
	v_mov_b32_e32 v208, 0
	v_mov_b32_e32 v209, 0
	v_cmp_gt_u32_e32 vcc, s51, v228
	s_and_saveexec_b64 s[30:31], vcc
	global_load_dwordx4 v[206:209], v[230:231], off offset:512
	s_mov_b64 exec, s[30:31]
	v_add_co_u32_e32 v230, vcc, 0x28000, v230
	s_nop 1
	v_addc_co_u32_e32 v231, vcc, 0, v231, vcc
	v_mov_b32_e32 v210, 0
	v_mov_b32_e32 v211, 0
	v_mov_b32_e32 v212, 0
	v_mov_b32_e32 v213, 0
	v_add_u32_e32 v229, 16, v228
	v_cmp_gt_u32_e32 vcc, s51, v229
	s_and_saveexec_b64 s[30:31], vcc
	global_load_dwordx4 v[210:213], v[230:231], off offset:512
	s_mov_b64 exec, s[30:31]
	v_add_co_u32_e32 v230, vcc, 0x28000, v230
	s_nop 1
	v_addc_co_u32_e32 v231, vcc, 0, v231, vcc
	v_mov_b32_e32 v214, 0
	v_mov_b32_e32 v215, 0
	v_mov_b32_e32 v216, 0
	v_mov_b32_e32 v217, 0
	v_add_u32_e32 v229, 32, v228
	v_cmp_gt_u32_e32 vcc, s51, v229
	s_and_saveexec_b64 s[30:31], vcc
	global_load_dwordx4 v[214:217], v[230:231], off offset:512
	s_mov_b64 exec, s[30:31]
	v_add_co_u32_e32 v230, vcc, 0x28000, v230
	s_nop 1
	v_addc_co_u32_e32 v231, vcc, 0, v231, vcc
	v_mov_b32_e32 v218, 0
	v_mov_b32_e32 v219, 0
	v_mov_b32_e32 v220, 0
	v_mov_b32_e32 v221, 0
	v_add_u32_e32 v229, 48, v228
	v_cmp_gt_u32_e32 vcc, s51, v229
	s_and_saveexec_b64 s[30:31], vcc
	global_load_dwordx4 v[218:221], v[230:231], off offset:512
	s_mov_b64 exec, s[30:31]
	v_add_co_u32_e32 v230, vcc, 0x28000, v230
	s_nop 1
	v_addc_co_u32_e32 v231, vcc, 0, v231, vcc
	v_mov_b32_e32 v222, 0
	v_mov_b32_e32 v223, 0
	v_mov_b32_e32 v224, 0
	v_mov_b32_e32 v225, 0
	v_add_u32_e32 v229, 64, v228
	v_cmp_gt_u32_e32 vcc, s51, v229
	s_and_saveexec_b64 s[30:31], vcc
	global_load_dwordx4 v[222:225], v[230:231], off offset:512
	s_mov_b64 exec, s[30:31]
	s_waitcnt vmcnt(0)
	ds_write_b128 v226, v[206:209]
	ds_write_b128 v226, v[210:213] offset:8448
	ds_write_b128 v226, v[214:217] offset:16896
	ds_write_b128 v226, v[218:221] offset:25344
	ds_write_b128 v226, v[222:225] offset:33792
